# PRO: transposed bf16 weight stores streamed (nt): first read hundreds of microseconds later, keep the cache for xg / Zt
# baseline (speedup 1.0000x reference)
.LBB0_27:
	s_waitcnt lgkmcnt(3)
	v_mov_b32_e32 v14, v9
	s_waitcnt lgkmcnt(2)
	v_mov_b32_e32 v15, v11
	v_pk_mul_f32 v[14:15], v[70:71], v[14:15]
	v_mov_b32_e32 v9, v10
	s_waitcnt lgkmcnt(1)
	v_mov_b32_e32 v10, v7
	s_waitcnt lgkmcnt(0)
	v_mov_b32_e32 v11, v13
	v_mov_b32_e32 v7, v12
	v_pk_mul_f32 v[10:11], v[66:67], v[10:11]
	v_pk_mul_f32 v[6:7], v[82:83], v[6:7]
	v_bfe_u32 v16, v14, 16, 1
	v_pk_mul_f32 v[8:9], v[84:85], v[8:9]
	v_bfe_u32 v12, v10, 16, 1
	v_add3_u32 v14, v14, v16, s76
	v_bfe_u32 v16, v7, 16, 1
	v_bfe_u32 v5, v11, 16, 1
	v_bfe_u32 v13, v15, 16, 1
	v_add3_u32 v10, v10, v12, s76
	v_bfe_u32 v12, v9, 16, 1
	v_add3_u32 v7, v7, v16, s76
	v_add3_u32 v13, v15, v13, s76
	v_add3_u32 v5, v11, v5, s76
	v_bfe_u32 v11, v8, 16, 1
	v_bfe_u32 v15, v6, 16, 1
	v_add3_u32 v9, v9, v12, s76
	v_lshrrev_b32_e32 v7, 16, v7
	v_add3_u32 v6, v6, v15, s76
	v_add3_u32 v8, v8, v11, s76
	v_lshrrev_b32_e32 v12, 16, v9
	v_and_or_b32 v9, v5, s77, v7
	v_ashrrev_i32_e32 v5, 31, v4
	v_lshrrev_b32_e32 v11, 16, v8
	v_lshrrev_b32_e32 v6, 16, v6
	v_lshlrev_b64 v[4:5], 12, v[4:5]
	v_and_or_b32 v8, v10, s77, v6
	v_and_or_b32 v7, v13, s77, v12
	v_and_or_b32 v6, v14, s77, v11
	v_lshl_add_u64 v[2:3], v[2:3], 0, v[4:5]
	global_store_dwordx4 v[2:3], v[6:9], off nt
	s_waitcnt lgkmcnt(0)
	v_mov_b64_e32 v[2:3], v[34:35]
	s_andn2_b64 vcc, exec, s[12:13]
	s_mov_b64 s[4:5], s[14:15]
	s_mov_b32 s34, s80
	v_mov_b32_e32 v92, v91
	s_mov_b32 s28, s79
	v_mov_b64_e32 v[4:5], v[36:37]
	v_mov_b64_e32 v[6:7], v[38:39]
	v_mov_b64_e32 v[8:9], v[40:41]
	v_mov_b64_e32 v[10:11], v[42:43]
	v_mov_b64_e32 v[12:13], v[44:45]
	v_mov_b64_e32 v[14:15], v[46:47]
	v_mov_b64_e32 v[16:17], v[48:49]
	v_mov_b64_e32 v[18:19], v[50:51]
	v_mov_b64_e32 v[20:21], v[52:53]
	v_mov_b64_e32 v[22:23], v[54:55]
	v_mov_b64_e32 v[24:25], v[56:57]
	v_mov_b64_e32 v[26:27], v[58:59]
	v_mov_b64_e32 v[28:29], v[60:61]
	v_mov_b64_e32 v[30:31], v[62:63]
	v_mov_b64_e32 v[32:33], v[64:65]
	v_mov_b32_e32 v82, v72
	v_mov_b32_e32 v66, v73
	v_mov_b32_e32 v83, v74
	v_mov_b32_e32 v67, v75
	v_mov_b32_e32 v84, v76
	v_mov_b32_e32 v70, v77
	v_mov_b32_e32 v85, v78
	v_mov_b32_e32 v71, v79
	s_cbranch_vccz .LBB0_64

.LBB0_58:
	v_pk_mul_f32 v[12:13], v[70:71], v[12:13]
	s_lshl_b32 s16, s10, 6
	v_pk_mul_f32 v[6:7], v[82:83], v[6:7]
	v_pk_mul_f32 v[8:9], v[66:67], v[8:9]
	v_bfe_u32 v17, v12, 16, 1
	s_ashr_i32 s17, s16, 31
	v_pk_mul_f32 v[10:11], v[84:85], v[10:11]
	v_bfe_u32 v5, v9, 16, 1
	v_add3_u32 v12, v12, v17, s76
	v_bfe_u32 v17, v7, 16, 1
	s_lshl_b64 s[16:17], s[16:17], 1
	v_bfe_u32 v15, v8, 16, 1
	v_bfe_u32 v16, v13, 16, 1
	v_add3_u32 v5, v9, v5, s76
	v_bfe_u32 v9, v10, 16, 1
	v_add3_u32 v7, v7, v17, s76
	s_add_u32 s4, s4, s16
	v_add3_u32 v13, v13, v16, s76
	v_add3_u32 v8, v8, v15, s76
	v_bfe_u32 v15, v11, 16, 1
	v_bfe_u32 v16, v6, 16, 1
	v_add3_u32 v9, v10, v9, s76
	v_lshrrev_b32_e32 v7, 16, v7
	s_addc_u32 s5, s5, s17
	v_add3_u32 v6, v6, v16, s76
	v_add3_u32 v11, v11, v15, s76
	v_lshrrev_b32_e32 v10, 16, v9
	v_and_or_b32 v9, v5, s77, v7
	v_ashrrev_i32_e32 v5, 31, v4
	v_lshl_add_u64 v[2:3], s[4:5], 0, v[86:87]
	v_lshrrev_b32_e32 v11, 16, v11
	v_lshrrev_b32_e32 v6, 16, v6
	v_lshlrev_b64 v[4:5], 12, v[4:5]
	v_and_or_b32 v8, v8, s77, v6
	v_and_or_b32 v7, v13, s77, v11
	v_and_or_b32 v6, v12, s77, v10
	v_lshl_add_u64 v[4:5], v[2:3], 0, v[4:5]
	global_store_dwordx4 v[4:5], v[6:9], off nt
	ds_read2_b32 v[6:7], v81 offset0:8 offset1:41
	ds_read2_b32 v[12:13], v81 offset0:74 offset1:107
	ds_read2_b32 v[8:9], v81 offset0:140 offset1:173
	ds_read2_b32 v[10:11], v81 offset0:206 offset1:239
	v_cndmask_b32_e64 v4, 0, 1, s[6:7]
	v_cmp_ne_u32_e64 s[4:5], 1, v4
	s_andn2_b64 vcc, exec, s[6:7]
	v_add_u32_e32 v4, 8, v14
	s_cbranch_vccnz .LBB0_60
	v_and_b32_e32 v5, 63, v4
	v_lshlrev_b32_e32 v15, 1, v5
	v_subrev_u32_e32 v16, 63, v15
	v_cmp_gt_u32_e32 vcc, 32, v5
	s_nop 1
	v_cndmask_b32_e32 v5, v16, v15, vcc
	v_and_b32_e32 v15, 0xffffffc0, v4
	v_add_u32_e32 v5, v5, v15
	v_cmp_lt_i32_e32 vcc, s71, v4
	s_nop 1
	v_cndmask_b32_e32 v4, v5, v4, vcc
.LBB0_60:
	s_waitcnt lgkmcnt(2)
	v_mov_b32_e32 v17, v12
	v_mov_b32_e32 v12, v7
	v_mov_b32_e32 v16, v6
	v_pk_mul_f32 v[6:7], v[70:71], v[12:13]
	s_waitcnt lgkmcnt(0)
	v_mov_b32_e32 v13, v10
	v_mov_b32_e32 v10, v9
	v_mov_b32_e32 v12, v8
	v_pk_mul_f32 v[8:9], v[66:67], v[10:11]
	v_pk_mul_f32 v[16:17], v[84:85], v[16:17]
	v_pk_mul_f32 v[12:13], v[82:83], v[12:13]
	v_bfe_u32 v5, v9, 16, 1
	v_bfe_u32 v10, v8, 16, 1
	v_bfe_u32 v11, v7, 16, 1
	v_bfe_u32 v15, v6, 16, 1
	v_add3_u32 v6, v6, v15, s76
	v_add3_u32 v7, v7, v11, s76
	v_add3_u32 v8, v8, v10, s76
	v_add3_u32 v5, v9, v5, s76
	v_bfe_u32 v9, v16, 16, 1
	v_bfe_u32 v10, v17, 16, 1
	v_bfe_u32 v11, v12, 16, 1
	v_bfe_u32 v15, v13, 16, 1
	v_add3_u32 v13, v13, v15, s76
	v_add3_u32 v11, v12, v11, s76
	v_add3_u32 v10, v17, v10, s76
	v_add3_u32 v9, v16, v9, s76
	v_lshrrev_b32_e32 v9, 16, v9
	v_lshrrev_b32_e32 v10, 16, v10
	v_lshrrev_b32_e32 v11, 16, v11
	v_lshrrev_b32_e32 v12, 16, v13
	v_and_or_b32 v19, v5, s77, v12
	v_and_or_b32 v18, v8, s77, v11
	v_and_or_b32 v17, v7, s77, v10
	v_and_or_b32 v16, v6, s77, v9
	ds_read2_b32 v[6:7], v81 offset0:16 offset1:49
	ds_read2_b32 v[12:13], v81 offset0:82 offset1:115
	ds_read2_b32 v[8:9], v81 offset0:148 offset1:181
	ds_read2_b32 v[10:11], v81 offset0:214 offset1:247
	v_ashrrev_i32_e32 v5, 31, v4
	v_lshlrev_b64 v[4:5], 12, v[4:5]
	v_lshl_add_u64 v[4:5], v[2:3], 0, v[4:5]
	global_store_dwordx4 v[4:5], v[16:19], off nt
	s_and_b64 vcc, exec, s[4:5]
	v_add_u32_e32 v4, 16, v14
	s_cbranch_vccnz .LBB0_62
	v_and_b32_e32 v5, 63, v4
	v_lshlrev_b32_e32 v15, 1, v5
	v_subrev_u32_e32 v16, 63, v15
	v_cmp_gt_u32_e32 vcc, 32, v5
	s_nop 1
	v_cndmask_b32_e32 v5, v16, v15, vcc
	v_and_b32_e32 v15, 0xffffffc0, v4
	v_add_u32_e32 v5, v5, v15
	v_cmp_lt_i32_e32 vcc, s71, v4
	s_nop 1
	v_cndmask_b32_e32 v4, v5, v4, vcc
.LBB0_62:
	s_waitcnt lgkmcnt(2)
	v_mov_b32_e32 v17, v12
	v_mov_b32_e32 v12, v7
	v_mov_b32_e32 v16, v6
	v_pk_mul_f32 v[6:7], v[70:71], v[12:13]
	s_waitcnt lgkmcnt(0)
	v_mov_b32_e32 v13, v10
	v_mov_b32_e32 v10, v9
	v_mov_b32_e32 v12, v8
	v_pk_mul_f32 v[8:9], v[66:67], v[10:11]
	v_pk_mul_f32 v[16:17], v[84:85], v[16:17]
	v_pk_mul_f32 v[12:13], v[82:83], v[12:13]
	v_bfe_u32 v5, v9, 16, 1
	v_bfe_u32 v10, v8, 16, 1
	v_bfe_u32 v11, v7, 16, 1
	v_bfe_u32 v15, v6, 16, 1
	v_add3_u32 v6, v6, v15, s76
	v_add3_u32 v7, v7, v11, s76
	v_add3_u32 v8, v8, v10, s76
	v_add3_u32 v5, v9, v5, s76
	v_bfe_u32 v9, v16, 16, 1
	v_bfe_u32 v10, v17, 16, 1
	v_bfe_u32 v11, v12, 16, 1
	v_bfe_u32 v15, v13, 16, 1
	v_add3_u32 v13, v13, v15, s76
	v_add3_u32 v11, v12, v11, s76
	v_add3_u32 v10, v17, v10, s76
	v_add3_u32 v9, v16, v9, s76
	v_lshrrev_b32_e32 v9, 16, v9
	v_lshrrev_b32_e32 v10, 16, v10
	v_lshrrev_b32_e32 v11, 16, v11
	v_lshrrev_b32_e32 v12, 16, v13
	v_and_or_b32 v19, v5, s77, v12
	v_and_or_b32 v18, v8, s77, v11
	v_and_or_b32 v17, v7, s77, v10
	v_and_or_b32 v16, v6, s77, v9
	ds_read2_b32 v[8:9], v81 offset0:24 offset1:57
	ds_read2_b32 v[10:11], v81 offset0:90 offset1:123
	ds_read2_b32 v[6:7], v81 offset0:156 offset1:189
	ds_read2_b32 v[12:13], v81 offset0:222 offset1:255
	v_ashrrev_i32_e32 v5, 31, v4
	v_lshlrev_b64 v[4:5], 12, v[4:5]
	v_lshl_add_u64 v[4:5], v[2:3], 0, v[4:5]
	global_store_dwordx4 v[4:5], v[16:19], off nt
	s_and_b64 vcc, exec, s[4:5]
	v_add_u32_e32 v4, 24, v14
	s_cbranch_vccnz .LBB0_27
	v_and_b32_e32 v5, 63, v4
	v_lshlrev_b32_e32 v14, 1, v5
	v_subrev_u32_e32 v15, 63, v14
	v_cmp_gt_u32_e32 vcc, 32, v5
	s_nop 1
	v_cndmask_b32_e32 v5, v15, v14, vcc
	v_and_b32_e32 v14, 0xffffffc0, v4
	v_add_u32_e32 v5, v5, v14
	v_cmp_lt_i32_e32 vcc, s71, v4
	s_nop 1
	v_cndmask_b32_e32 v4, v5, v4, vcc
	s_branch .LBB0_27
